# chain v5b: loaders keep two steps landed ahead, next-step operand reads issued in the MFMA shadows before the barrier, previous step y rows stored just before the barrier
# baseline (speedup 1.0000x reference)
.LBB0_406:
	v_and_b32_e32 v1, 63, v0
	v_and_b32_e32 v2, 15, v1
	v_lshrrev_b32_e32 v3, 4, v1
	v_readfirstlane_b32 s6, v0
	s_lshr_b32 s7, s2, 4
	s_and_b32 s8, s2, 15
	s_nop 0
	s_lshr_b32 s6, s6, 6
	s_cmp_gt_u32 s6, 3
	s_cbranch_scc1 .Lser_loader
	v_lshrrev_b32_e32 v4, 1, v3
	v_and_b32_e32 v5, 1, v3
	v_lshlrev_b32_e32 v4, 8, v4
	v_lshl_add_u32 v4, v2, 4, v4
	v_lshl_add_u32 v4, v5, 3, v4
	s_lshl_b32 s12, s6, 4
	v_add_u32_e32 v5, s12, v2
	v_lshlrev_b32_e32 v6, 5, v5
	v_lshl_add_u32 v6, v3, 3, v6
	v_add_u32_e32 v6, 0x2400, v6
	v_lshlrev_b32_e32 v7, 9, v3
	v_lshl_add_u32 v7, v5, 1, v7
	v_add_u32_e32 v7, 0x2c00, v7
	v_lshrrev_b32_e32 v120, 2, v2
	v_lshlrev_b32_e32 v120, 6, v120
	v_lshl_add_u32 v120, v3, 4, v120
	v_and_b32_e32 v129, 3, v2
	v_lshl_add_u32 v120, v129, 2, v120
	v_add_u32_e32 v120, 0x3400, v120
	v_lshlrev_b32_e32 v116, 13, v3
	v_lshl_add_u32 v116, v5, 1, v116
	s_lshl_b32 s12, s7, 23
	s_lshl_b32 s13, s8, 7
	s_add_u32 s12, s12, s13
	s_add_u32 s12, s12, 0x14a00000
	v_add_u32_e32 v116, s12, v116
	v_mov_b32_e32 v117, 0
	s_mov_b64 s[14:15], 0x1000
	s_mov_b64 s[16:17], 0x8000
	v_lshl_add_u64 v[116:117], v[116:117], 0, s[70:71]
	v_lshl_add_u64 v[118:119], v[116:117], 0, s[14:15]
	v_mov_b32_e32 v8, 0
	v_mov_b32_e32 v9, 0
	v_mov_b32_e32 v10, 0
	v_mov_b32_e32 v11, 0
	v_mov_b32_e32 v12, 0
	v_mov_b32_e32 v13, 0
	v_mov_b32_e32 v14, 0
	v_mov_b32_e32 v15, 0
	v_mov_b32_e32 v16, 0
	v_mov_b32_e32 v17, 0
	v_mov_b32_e32 v18, 0
	v_mov_b32_e32 v19, 0
	v_mov_b32_e32 v20, 0
	v_mov_b32_e32 v21, 0
	v_mov_b32_e32 v22, 0
	v_mov_b32_e32 v23, 0
	v_mov_b32_e32 v24, 0
	v_mov_b32_e32 v25, 0
	v_mov_b32_e32 v26, 0
	v_mov_b32_e32 v27, 0
	v_mov_b32_e32 v28, 0
	v_mov_b32_e32 v29, 0
	v_mov_b32_e32 v30, 0
	v_mov_b32_e32 v31, 0
	s_mov_b32 s10, 0
	s_mov_b32 s11, 0
	s_mov_b64 s[18:19], 0
	s_barrier
	v_add_u32_e32 v121, s10, v4
	v_add_u32_e32 v126, s10, v6
	v_add_u32_e32 v128, s10, v120
	v_add_u32_e32 v122, 0x800, v121
	ds_read_b64 v[48:49], v126
	ds_read2_b64 v[32:35], v121 offset1:64
	ds_read2_b64 v[36:39], v121 offset0:128 offset1:192
	ds_read2_b64 v[40:43], v122 offset1:64
	ds_read2_b64 v[44:47], v122 offset0:128 offset1:192
	ds_read_b32 v82, v128
	v_add_u32_e32 v127, s10, v7
	v_add_u32_e32 v123, 0x1000, v121
	v_add_u32_e32 v124, 0x1800, v121
	v_add_u32_e32 v125, 0x2000, v121
	ds_read_u16 v133, v127
	ds_read_u16 v134, v127 offset:128
	ds_read_u16 v135, v127 offset:256
	ds_read_u16 v136, v127 offset:384
	ds_read2_b64 v[62:65], v123 offset1:64
	ds_read2_b64 v[66:69], v123 offset0:128 offset1:192
	ds_read2_b64 v[70:73], v124 offset1:64
	ds_read2_b64 v[74:77], v124 offset0:128 offset1:192
	ds_read2_b64 v[78:81], v125 offset1:64
	s_add_u32 s10, s10, 0x3800
	s_cmp_eq_u32 s10, 0x1c000
	s_cselect_b32 s10, 0, s10
	s_waitcnt lgkmcnt(9)
	v_lshlrev_b32_e32 v50, 16, v48
	v_and_b32_e32 v51, 0xffff0000, v48
	v_lshlrev_b32_e32 v52, 16, v49
	v_and_b32_e32 v53, 0xffff0000, v49
.Lser_chain_loop:
	s_nop 1
	v_mfma_f32_16x16x32_bf16 v[50:53], v[32:35], v[24:27], v[50:53]
	v_add_u32_e32 v121, s10, v4
	v_add_u32_e32 v126, s10, v6
	v_add_u32_e32 v128, s10, v120
	v_mfma_f32_16x16x32_bf16 v[54:57], v[40:43], v[24:27], 0
	v_add_u32_e32 v122, 0x800, v121
	ds_read_b64 v[140:141], v126
	ds_read2_b64 v[142:145], v121 offset1:64
	v_mfma_f32_16x16x32_bf16 v[50:53], v[36:39], v[28:31], v[50:53]
	ds_read2_b64 v[146:149], v121 offset0:128 offset1:192
	ds_read2_b64 v[150:153], v122 offset1:64
	ds_read2_b64 v[154:157], v122 offset0:128 offset1:192
	v_mfma_f32_16x16x32_bf16 v[54:57], v[44:47], v[28:31], v[54:57]
	ds_read_b32 v158, v128
	v_mul_f32_dpp v98, v82, v8 row_newbcast:0 row_mask:0xf bank_mask:0xf
	v_mul_f32_dpp v99, v82, v9 row_newbcast:1 row_mask:0xf bank_mask:0xf
	v_mul_f32_dpp v100, v82, v10 row_newbcast:2 row_mask:0xf bank_mask:0xf
	v_mul_f32_dpp v101, v82, v11 row_newbcast:3 row_mask:0xf bank_mask:0xf
	v_mul_f32_dpp v102, v82, v12 row_newbcast:4 row_mask:0xf bank_mask:0xf
	v_mul_f32_dpp v103, v82, v13 row_newbcast:5 row_mask:0xf bank_mask:0xf
	v_mul_f32_dpp v104, v82, v14 row_newbcast:6 row_mask:0xf bank_mask:0xf
	v_mul_f32_dpp v105, v82, v15 row_newbcast:7 row_mask:0xf bank_mask:0xf
	v_mul_f32_dpp v106, v82, v16 row_newbcast:8 row_mask:0xf bank_mask:0xf
	v_mul_f32_dpp v107, v82, v17 row_newbcast:9 row_mask:0xf bank_mask:0xf
	v_mul_f32_dpp v108, v82, v18 row_newbcast:10 row_mask:0xf bank_mask:0xf
	v_mul_f32_dpp v109, v82, v19 row_newbcast:11 row_mask:0xf bank_mask:0xf
	v_mul_f32_dpp v110, v82, v20 row_newbcast:12 row_mask:0xf bank_mask:0xf
	v_mul_f32_dpp v111, v82, v21 row_newbcast:13 row_mask:0xf bank_mask:0xf
	v_mul_f32_dpp v112, v82, v22 row_newbcast:14 row_mask:0xf bank_mask:0xf
	v_mul_f32_dpp v113, v82, v23 row_newbcast:15 row_mask:0xf bank_mask:0xf
	v_cvt_pk_bf16_f32 v114, v204, v204
	v_cvt_pk_bf16_f32 v115, v205, v205
	v_cvt_pk_bf16_f32 v131, v206, v206
	v_cvt_pk_bf16_f32 v132, v207, v207
	s_mov_b64 exec, s[18:19]
	global_store_short v[116:117], v114, off
	global_store_short v[116:117], v115, off offset:2048
	global_store_short v[118:119], v131, off
	global_store_short v[118:119], v132, off offset:2048
	s_mov_b64 exec, -1
	v_lshl_add_u64 v[116:117], v[116:117], 0, s[16:17]
	v_lshl_add_u64 v[118:119], v[118:119], 0, s[16:17]
	s_barrier
	v_cvt_pk_bf16_f32 v58, v50, v51
	v_cvt_pk_bf16_f32 v59, v52, v53
	s_waitcnt lgkmcnt(6)
	v_lshl_or_b32 v60, v134, 16, v133
	v_lshl_or_b32 v61, v136, 16, v135
	s_nop 1
	v_mfma_f32_16x16x32_bf16 v[8:11], v[62:65], v[58:61], v[98:101]
	v_add_u32_e32 v127, s10, v7
	v_add_u32_e32 v123, 0x1000, v121
	v_add_u32_e32 v124, 0x1800, v121
	v_mfma_f32_16x16x32_bf16 v[12:15], v[66:69], v[58:61], v[102:105]
	v_add_u32_e32 v125, 0x2000, v121
	ds_read_u16 v174, v127
	ds_read_u16 v175, v127 offset:128
	v_mfma_f32_16x16x32_bf16 v[16:19], v[70:73], v[58:61], v[106:109]
	ds_read_u16 v176, v127 offset:256
	ds_read_u16 v177, v127 offset:384
	ds_read2_b64 v[184:187], v123 offset1:64
	v_mfma_f32_16x16x32_bf16 v[20:23], v[74:77], v[58:61], v[110:113]
	ds_read2_b64 v[188:191], v123 offset0:128 offset1:192
	ds_read2_b64 v[192:195], v124 offset1:64
	ds_read2_b64 v[196:199], v124 offset0:128 offset1:192
	v_mfma_f32_16x16x32_bf16 v[54:57], v[78:81], v[58:61], v[54:57]
	ds_read2_b64 v[200:203], v125 offset1:64
	s_add_u32 s10, s10, 0x3800
	s_cmp_eq_u32 s10, 0x1c000
	s_cselect_b32 s10, 0, s10
	v_cvt_pk_bf16_f32 v24, v8, v9
	v_cvt_pk_bf16_f32 v25, v10, v11
	v_cvt_pk_bf16_f32 v26, v12, v13
	v_cvt_pk_bf16_f32 v27, v14, v15
	v_cvt_pk_bf16_f32 v28, v16, v17
	v_cvt_pk_bf16_f32 v29, v18, v19
	v_cvt_pk_bf16_f32 v30, v20, v21
	v_cvt_pk_bf16_f32 v31, v22, v23
	s_waitcnt lgkmcnt(9)
	v_lshlrev_b32_e32 v50, 16, v140
	v_and_b32_e32 v51, 0xffff0000, v140
	v_lshlrev_b32_e32 v52, 16, v141
	v_and_b32_e32 v53, 0xffff0000, v141
	s_nop 1
	v_mfma_f32_16x16x32_bf16 v[50:53], v[142:145], v[24:27], v[50:53]
	v_add_u32_e32 v121, s10, v4
	v_add_u32_e32 v126, s10, v6
	v_add_u32_e32 v128, s10, v120
	v_mfma_f32_16x16x32_bf16 v[204:207], v[150:153], v[24:27], 0
	v_add_u32_e32 v122, 0x800, v121
	ds_read_b64 v[48:49], v126
	ds_read2_b64 v[32:35], v121 offset1:64
	v_mfma_f32_16x16x32_bf16 v[50:53], v[146:149], v[28:31], v[50:53]
	ds_read2_b64 v[36:39], v121 offset0:128 offset1:192
	ds_read2_b64 v[40:43], v122 offset1:64
	ds_read2_b64 v[44:47], v122 offset0:128 offset1:192
	v_mfma_f32_16x16x32_bf16 v[204:207], v[154:157], v[28:31], v[204:207]
	ds_read_b32 v82, v128
	v_mul_f32_dpp v98, v158, v8 row_newbcast:0 row_mask:0xf bank_mask:0xf
	v_mul_f32_dpp v99, v158, v9 row_newbcast:1 row_mask:0xf bank_mask:0xf
	v_mul_f32_dpp v100, v158, v10 row_newbcast:2 row_mask:0xf bank_mask:0xf
	v_mul_f32_dpp v101, v158, v11 row_newbcast:3 row_mask:0xf bank_mask:0xf
	v_mul_f32_dpp v102, v158, v12 row_newbcast:4 row_mask:0xf bank_mask:0xf
	v_mul_f32_dpp v103, v158, v13 row_newbcast:5 row_mask:0xf bank_mask:0xf
	v_mul_f32_dpp v104, v158, v14 row_newbcast:6 row_mask:0xf bank_mask:0xf
	v_mul_f32_dpp v105, v158, v15 row_newbcast:7 row_mask:0xf bank_mask:0xf
	v_mul_f32_dpp v106, v158, v16 row_newbcast:8 row_mask:0xf bank_mask:0xf
	v_mul_f32_dpp v107, v158, v17 row_newbcast:9 row_mask:0xf bank_mask:0xf
	v_mul_f32_dpp v108, v158, v18 row_newbcast:10 row_mask:0xf bank_mask:0xf
	v_mul_f32_dpp v109, v158, v19 row_newbcast:11 row_mask:0xf bank_mask:0xf
	v_mul_f32_dpp v110, v158, v20 row_newbcast:12 row_mask:0xf bank_mask:0xf
	v_mul_f32_dpp v111, v158, v21 row_newbcast:13 row_mask:0xf bank_mask:0xf
	v_mul_f32_dpp v112, v158, v22 row_newbcast:14 row_mask:0xf bank_mask:0xf
	v_mul_f32_dpp v113, v158, v23 row_newbcast:15 row_mask:0xf bank_mask:0xf
	v_cvt_pk_bf16_f32 v114, v54, v54
	v_cvt_pk_bf16_f32 v115, v55, v55
	v_cvt_pk_bf16_f32 v131, v56, v56
	v_cvt_pk_bf16_f32 v132, v57, v57
	global_store_short v[116:117], v114, off
	global_store_short v[116:117], v115, off offset:2048
	global_store_short v[118:119], v131, off
	global_store_short v[118:119], v132, off offset:2048
	v_lshl_add_u64 v[116:117], v[116:117], 0, s[16:17]
	v_lshl_add_u64 v[118:119], v[118:119], 0, s[16:17]
	s_barrier
	v_cvt_pk_bf16_f32 v180, v50, v51
	v_cvt_pk_bf16_f32 v181, v52, v53
	s_waitcnt lgkmcnt(6)
	v_lshl_or_b32 v182, v175, 16, v174
	v_lshl_or_b32 v183, v177, 16, v176
	s_nop 1
	v_mfma_f32_16x16x32_bf16 v[8:11], v[184:187], v[180:183], v[98:101]
	v_add_u32_e32 v127, s10, v7
	v_add_u32_e32 v123, 0x1000, v121
	v_add_u32_e32 v124, 0x1800, v121
	v_mfma_f32_16x16x32_bf16 v[12:15], v[188:191], v[180:183], v[102:105]
	v_add_u32_e32 v125, 0x2000, v121
	ds_read_u16 v133, v127
	ds_read_u16 v134, v127 offset:128
	v_mfma_f32_16x16x32_bf16 v[16:19], v[192:195], v[180:183], v[106:109]
	ds_read_u16 v135, v127 offset:256
	ds_read_u16 v136, v127 offset:384
	ds_read2_b64 v[62:65], v123 offset1:64
	v_mfma_f32_16x16x32_bf16 v[20:23], v[196:199], v[180:183], v[110:113]
	ds_read2_b64 v[66:69], v123 offset0:128 offset1:192
	ds_read2_b64 v[70:73], v124 offset1:64
	ds_read2_b64 v[74:77], v124 offset0:128 offset1:192
	v_mfma_f32_16x16x32_bf16 v[204:207], v[200:203], v[180:183], v[204:207]
	ds_read2_b64 v[78:81], v125 offset1:64
	s_add_u32 s10, s10, 0x3800
	s_cmp_eq_u32 s10, 0x1c000
	s_cselect_b32 s10, 0, s10
	v_cvt_pk_bf16_f32 v24, v8, v9
	v_cvt_pk_bf16_f32 v25, v10, v11
	v_cvt_pk_bf16_f32 v26, v12, v13
	v_cvt_pk_bf16_f32 v27, v14, v15
	v_cvt_pk_bf16_f32 v28, v16, v17
	v_cvt_pk_bf16_f32 v29, v18, v19
	v_cvt_pk_bf16_f32 v30, v20, v21
	v_cvt_pk_bf16_f32 v31, v22, v23
	s_waitcnt lgkmcnt(9)
	v_lshlrev_b32_e32 v50, 16, v48
	v_and_b32_e32 v51, 0xffff0000, v48
	v_lshlrev_b32_e32 v52, 16, v49
	v_and_b32_e32 v53, 0xffff0000, v49
	s_mov_b64 s[18:19], -1
	s_add_u32 s11, s11, 2
	s_cmp_lt_u32 s11, 0x100
	s_cbranch_scc1 .Lser_chain_loop
	s_waitcnt lgkmcnt(0)
	s_nop 7
	v_cvt_pk_bf16_f32 v114, v204, v204
	v_cvt_pk_bf16_f32 v115, v205, v205
	v_cvt_pk_bf16_f32 v131, v206, v206
	v_cvt_pk_bf16_f32 v132, v207, v207
	global_store_short v[116:117], v114, off
	global_store_short v[116:117], v115, off offset:2048
	global_store_short v[118:119], v131, off
	global_store_short v[118:119], v132, off offset:2048
	v_lshl_add_u64 v[116:117], v[116:117], 0, s[16:17]
	v_lshl_add_u64 v[118:119], v[118:119], 0, s[16:17]
	s_branch .Lser_exit

.Lser_ld_pro:
	s_cmp_lt_u32 s29, 0xff
	s_cselect_b32 s72, s20, 0
	s_cselect_b32 s73, s21, 0
	s_cselect_b32 s74, s22, 0
	s_cselect_b32 s75, s23, 0
	s_add_u32 m0, s28, s24
	s_nop 0
	global_load_lds_dwordx4 v10, s[12:13]
	s_add_u32 s12, s12, s72
	s_addc_u32 s13, s13, 0
	s_add_u32 m0, s28, s25
	s_nop 0
	global_load_lds_dwordx4 v11, s[14:15]
	s_add_u32 s14, s14, s73
	s_addc_u32 s15, s15, 0
	s_add_u32 m0, s28, s26
	s_nop 0
	global_load_lds_dwordx4 v12, s[16:17]
	s_add_u32 s16, s16, s74
	s_addc_u32 s17, s17, 0
	s_add_u32 m0, s28, s27
	s_nop 0
	global_load_lds_dwordx4 v13, s[18:19]
	s_add_u32 s18, s18, s75
	s_addc_u32 s19, s19, 0
	s_add_u32 s28, s28, 0x3800
	s_cmp_eq_u32 s28, 0x1c000
	s_cselect_b32 s28, 0, s28
	s_add_u32 s29, s29, 1
	s_cmp_lt_u32 s29, 7
	s_cbranch_scc1 .Lser_ld_pro
	s_waitcnt vmcnt(20)
	s_barrier
	s_mov_b32 s3, 0
.Lser_ld_loop:
	s_waitcnt vmcnt(16)
	s_barrier
	s_cmp_lt_u32 s29, 0xff
	s_cselect_b32 s72, s20, 0
	s_cselect_b32 s73, s21, 0
	s_cselect_b32 s74, s22, 0
	s_cselect_b32 s75, s23, 0
	s_add_u32 m0, s28, s24
	s_nop 0
	global_load_lds_dwordx4 v10, s[12:13]
	s_add_u32 s12, s12, s72
	s_addc_u32 s13, s13, 0
	s_add_u32 m0, s28, s25
	s_nop 0
	global_load_lds_dwordx4 v11, s[14:15]
	s_add_u32 s14, s14, s73
	s_addc_u32 s15, s15, 0
	s_add_u32 m0, s28, s26
	s_nop 0
	global_load_lds_dwordx4 v12, s[16:17]
	s_add_u32 s16, s16, s74
	s_addc_u32 s17, s17, 0
	s_add_u32 m0, s28, s27
	s_nop 0
	global_load_lds_dwordx4 v13, s[18:19]
	s_add_u32 s18, s18, s75
	s_addc_u32 s19, s19, 0
	s_add_u32 s28, s28, 0x3800
	s_cmp_eq_u32 s28, 0x1c000
	s_cselect_b32 s28, 0, s28
	s_add_u32 s29, s29, 1
	s_add_u32 s3, s3, 1
	s_cmp_lt_u32 s3, 0x100
	s_cbranch_scc1 .Lser_ld_loop
	s_waitcnt vmcnt(0)
	s_branch .Lser_exit
.Lser_ld3_pro:
	s_cmp_lt_u32 s29, 0xff
	s_cselect_b32 s72, s20, 0
	s_cselect_b32 s73, s21, 0
	s_add_u32 m0, s28, s24
	s_nop 0
	global_load_lds_dwordx4 v10, s[12:13]
	s_add_u32 s12, s12, s72
	s_addc_u32 s13, s13, 0
	s_add_u32 m0, s28, s25
	s_nop 0
	global_load_lds_dwordx4 v11, s[14:15]
	s_add_u32 s14, s14, s73
	s_addc_u32 s15, s15, 0
	s_add_u32 s28, s28, 0x3800
	s_cmp_eq_u32 s28, 0x1c000
	s_cselect_b32 s28, 0, s28
	s_add_u32 s29, s29, 1
	s_cmp_lt_u32 s29, 7
	s_cbranch_scc1 .Lser_ld3_pro
	s_waitcnt vmcnt(10)
	s_barrier
	s_mov_b32 s3, 0
.Lser_ld3_loop:
	s_waitcnt vmcnt(8)
	s_barrier
	s_cmp_lt_u32 s29, 0xff
	s_cselect_b32 s72, s20, 0
	s_cselect_b32 s73, s21, 0
	s_add_u32 m0, s28, s24
	s_nop 0
	global_load_lds_dwordx4 v10, s[12:13]
	s_add_u32 s12, s12, s72
	s_addc_u32 s13, s13, 0
	s_add_u32 m0, s28, s25
	s_nop 0
	global_load_lds_dwordx4 v11, s[14:15]
	s_add_u32 s14, s14, s73
	s_addc_u32 s15, s15, 0
	s_add_u32 s28, s28, 0x3800
	s_cmp_eq_u32 s28, 0x1c000
	s_cselect_b32 s28, 0, s28
	s_add_u32 s29, s29, 1
	s_add_u32 s3, s3, 1
	s_cmp_lt_u32 s3, 0x100
	s_cbranch_scc1 .Lser_ld3_loop
	s_waitcnt vmcnt(0)
